# strategy 7.2 waits to first consumer: redundant vmcnt(0) at the end of the attention unit prologues removed (the loop-top wait covers the Q loads and first DMA)
# baseline (speedup 1.0000x reference)
; #define LAS __attribute__((address_space(3)))
; #define ATT_ISSUE2(p_, st_) do { LAS unsigned char* sp_ = lds + (st_) * STG2; const int ta_ = dual ? (p_) : 2 * (p_), tb_ = dual ? (p_) : 2 * (p_) + 1; ATT_ISSUE1(u, ta_, sp_); ATT_ISSUEM(ta_, sp_ + 2 * STAGEB); \
;         if (dual || tb_ < u.ntiles) { ATT_ISSUE1(ub, tb_, sp_ + STAGEB); ATT_ISSUEM(tb_, sp_ + 2 * STAGEB + MSKB); } } while (0)
;     ...
;     const char* mbase = (const char*)(F.ws + WS_MASK); const unsigned moff = (unsigned)qrow * (MASKW * 4u);
;     f32x16 o[4];
; #pragma unroll
;     for (int d = 0; d < 4; ++d)
; #pragma unroll
;         for (int r = 0; r < 16; ++r) o[d][r] = 0.f;
;     float mrun = -1e30f, lrun = 0.f;
;     LAS unsigned char* lds = F.lds;
;     const int Lq = L >> 2, vlane = (4 * hi + Lq) * VSTR + 8 * (L & 1);
;     int voff[4][2];
; #pragma unroll
;     for (int d = 0; d < 4; ++d)
; #pragma unroll
;         for (int jj = 0; jj < 2; ++jj) voff[d][jj] = ((((d ^ Lq) << 2) | ((2 * ((lane >> 4) & 1) + ((L & 3) >> 1)) ^ (2 * jj + hi))) << 4);
;     const int ksw = r32 & 15;
;     v4u raw[4];
;     const int T0 = u.t0;
;     ...
;         const int npairs = dual ? u.ntiles : (u.ntiles + 1) >> 1, p0 = dual ? T0 : T0 >> 1;
;         ATT_ISSUE2(p0, p0 & 1);
;         for (int p = p0; p < npairs; ++p) {
;             asm volatile("s_waitcnt vmcnt(0)" ::: "memory");
;             __builtin_amdgcn_s_barrier(); asm volatile("" ::: "memory");
;             if (p + 1 < npairs) ATT_ISSUE2(p + 1, (p + 1) & 1);
.LBB0_577:
	s_add_i32 s1, s75, 1
	s_lshr_b32 s8, s1, 1
	s_lshr_b32 s2, s74, 1
	s_cmp_ge_u32 s2, s8
	s_cbranch_scc1 .LBB0_596
	v_lshrrev_b32_e32 v9, 3, v171
	v_and_b32_e32 v9, 2, v9
	v_bfe_u32 v10, v171, 1, 1
	v_or_b32_e32 v11, v9, v10
	v_lshrrev_b32_e32 v6, 2, v5
	v_bitop3_b32 v9, v9, v185, v10 bitop3:0x36
	v_bitop3_b32 v10, v185, v11, 2 bitop3:0x36
	v_lshlrev_b32_e32 v7, 8, v6
	v_lshlrev_b32_e32 v8, 3, v171
	v_lshlrev_b32_e32 v9, 4, v9
	v_lshlrev_b32_e32 v6, 6, v6
	v_lshlrev_b32_e32 v10, 4, v10
	v_and_b32_e32 v8, 8, v8
	v_or_b32_e32 v186, v9, v6
	v_or_b32_e32 v187, v10, v6
	v_bitop3_b32 v188, v9, v6, 64 bitop3:0xf6
	v_bitop3_b32 v189, v10, v6, 64 bitop3:0xf6
	v_bitop3_b32 v190, v9, v6, s66 bitop3:0xf6
	v_bitop3_b32 v191, v10, v6, s66 bitop3:0xf6
	v_bitop3_b32 v192, v9, v6, s67 bitop3:0xf6
	v_bitop3_b32 v193, v10, v6, s67 bitop3:0xf6
	v_lshlrev_b32_e32 v6, 10, v185
	v_or3_b32 v194, v6, v7, v8
	v_lshlrev_b32_e32 v195, 8, v4
	v_or_b32_e32 v4, s55, v185
	v_bitop3_b32 v6, v185, v5, s55 bitop3:0x36
	v_readlane_b32 s1, v254, 35
	v_lshlrev_b32_e32 v196, 4, v6
	v_bitop3_b32 v6, v4, v5, 2 bitop3:0x36
	s_or_b32 s9, s86, s1
	v_lshlrev_b32_e32 v197, 4, v6
	v_bitop3_b32 v6, v4, v5, 4 bitop3:0x36
	v_bitop3_b32 v4, v4, v5, 6 bitop3:0x36
	s_lshl_b32 s1, s2, 7
	v_mov_b32_e32 v52, v3
	v_mov_b32_e32 v53, v3
	v_mov_b32_e32 v66, v3
	v_mov_b32_e32 v67, v3
	v_lshlrev_b32_e32 v198, 4, v6
	v_lshlrev_b32_e32 v199, 4, v4
	s_add_i32 s1, s3, s1
	v_mov_b32_e32 v54, v3
	v_mov_b32_e32 v55, v3
	v_mov_b32_e32 v56, v3
	v_mov_b32_e32 v57, v3
	v_mov_b32_e32 v58, v3
	v_mov_b32_e32 v59, v3
	v_mov_b32_e32 v60, v3
	v_mov_b32_e32 v61, v3
	v_mov_b32_e32 v62, v3
	v_mov_b32_e32 v63, v3
	v_mov_b32_e32 v64, v3
	v_mov_b32_e32 v65, v3
	v_mov_b64_e32 v[36:37], v[52:53]
	v_mov_b64_e32 v[20:21], v[52:53]
	v_mov_b64_e32 v[4:5], v[52:53]
	v_mov_b64_e32 v[82:83], v[66:67]
	v_mov_b64_e32 v[114:115], v[66:67]
	v_readlane_b32 s36, v254, 29
	s_addk_i32 s0, 0xc0
	s_add_i32 s4, s1, 0x80
	v_mov_b32_e32 v170, 0xf149f2ca
	v_mov_b32_e32 v167, 0
	v_mov_b64_e32 v[38:39], v[54:55]
	v_mov_b64_e32 v[40:41], v[56:57]
	v_mov_b64_e32 v[42:43], v[58:59]
	v_mov_b64_e32 v[44:45], v[60:61]
	v_mov_b64_e32 v[46:47], v[62:63]
	v_mov_b64_e32 v[48:49], v[64:65]
	v_mov_b64_e32 v[50:51], v[66:67]
	v_mov_b64_e32 v[22:23], v[54:55]
	v_mov_b64_e32 v[24:25], v[56:57]
	v_mov_b64_e32 v[26:27], v[58:59]
	v_mov_b64_e32 v[28:29], v[60:61]
	v_mov_b64_e32 v[30:31], v[62:63]
	v_mov_b64_e32 v[32:33], v[64:65]
	v_mov_b64_e32 v[34:35], v[66:67]
	v_mov_b64_e32 v[6:7], v[54:55]
	v_mov_b64_e32 v[8:9], v[56:57]
	v_mov_b64_e32 v[10:11], v[58:59]
	v_mov_b64_e32 v[12:13], v[60:61]
	v_mov_b64_e32 v[14:15], v[62:63]
	v_mov_b64_e32 v[16:17], v[64:65]
	v_mov_b64_e32 v[18:19], v[66:67]
	v_mov_b64_e32 v[80:81], v[64:65]
	v_mov_b64_e32 v[78:79], v[62:63]
	v_mov_b64_e32 v[76:77], v[60:61]
	v_mov_b64_e32 v[74:75], v[58:59]
	v_mov_b64_e32 v[72:73], v[56:57]
	v_mov_b64_e32 v[70:71], v[54:55]
	v_mov_b64_e32 v[68:69], v[52:53]
	v_mov_b64_e32 v[112:113], v[64:65]
	v_mov_b64_e32 v[110:111], v[62:63]
	v_mov_b64_e32 v[108:109], v[60:61]
	v_mov_b64_e32 v[106:107], v[58:59]
	v_mov_b64_e32 v[104:105], v[56:57]
	v_mov_b64_e32 v[102:103], v[54:55]
	v_mov_b64_e32 v[100:101], v[52:53]
	v_readlane_b32 s37, v254, 30
.LBB0_579:
	s_add_i32 s27, s2, 1
	s_cmp_ge_u32 s27, s8
	s_cselect_b64 s[6:7], -1, 0
	s_and_b64 vcc, exec, s[6:7]
	s_cbranch_vccnz .Lpb2_done
	s_bitcmp1_b32 s27, 0
	s_cselect_b32 s1, 0x10400, 0
	s_ashr_i32 s5, s4, 31
	s_lshl_b64 s[28:29], s[4:5], 12
	s_add_i32 s1, s1, 0
	s_add_i32 s34, s74, 3
	s_or_b64 s[28:29], s[28:29], s[10:11]
	s_add_u32 s30, s56, s28
	s_addc_u32 s31, s57, s29
	s_add_u32 s28, s49, s28
	s_addc_u32 s29, s50, s29
	s_add_i32 s3, s1, s61
	s_add_i32 s5, s1, s63
	s_ashr_i32 s1, s0, 31
	s_lshl_b64 s[100:101], s[0:1], 12
	s_or_b64 s[100:101], s[100:101], s[10:11]
	s_add_u32 s98, s56, s100
	s_addc_u32 s99, s57, s101
	s_add_u32 s100, s49, s100
	s_addc_u32 s101, s50, s101

; #define LAS __attribute__((address_space(3)))
; #define ATT_ISSUE2(p_, st_) do { LAS unsigned char* sp_ = lds + (st_) * STG2; const int ta_ = dual ? (p_) : 2 * (p_), tb_ = dual ? (p_) : 2 * (p_) + 1; ATT_ISSUE1(u, ta_, sp_); ATT_ISSUEM(ta_, sp_ + 2 * STAGEB); \
;         if (dual || tb_ < u.ntiles) { ATT_ISSUE1(ub, tb_, sp_ + STAGEB); ATT_ISSUEM(tb_, sp_ + 2 * STAGEB + MSKB); } } while (0)
;     ...
;     const char* mbase = (const char*)(F.ws + WS_MASK); const unsigned moff = (unsigned)qrow * (MASKW * 4u);
;     f32x16 o[4];
; #pragma unroll
;     for (int d = 0; d < 4; ++d)
; #pragma unroll
;         for (int r = 0; r < 16; ++r) o[d][r] = 0.f;
;     float mrun = -1e30f, lrun = 0.f;
;     LAS unsigned char* lds = F.lds;
;     const int Lq = L >> 2, vlane = (4 * hi + Lq) * VSTR + 8 * (L & 1);
;     int voff[4][2];
; #pragma unroll
;     for (int d = 0; d < 4; ++d)
; #pragma unroll
;         for (int jj = 0; jj < 2; ++jj) voff[d][jj] = ((((d ^ Lq) << 2) | ((2 * ((lane >> 4) & 1) + ((L & 3) >> 1)) ^ (2 * jj + hi))) << 4);
;     const int ksw = r32 & 15;
;     v4u raw[4];
;     const int T0 = u.t0;
;     ...
;         const AttnUnit& ub = dual ? u2 : u;
;         const int npairs = dual ? u.ntiles : (u.ntiles + 1) >> 1, p0 = dual ? T0 : T0 >> 1;
;         ATT_ISSUE2(p0, p0 & 1);
;         for (int p = p0; p < npairs; ++p) {
;             asm volatile("s_waitcnt vmcnt(0)" ::: "memory");
;             __builtin_amdgcn_s_barrier(); asm volatile("" ::: "memory");
;             if (p + 1 < npairs) ATT_ISSUE2(p + 1, (p + 1) & 1);
.LBB0_3299:
	s_add_i32 s3, s89, 1
	s_lshr_b32 s3, s3, 1
	s_and_b64 s[4:5], s[24:25], exec
	s_cselect_b32 s21, s3, s89
	s_cmp_ge_u32 s97, s21
	s_cbranch_scc1 .LBB0_3330
	s_or_b32 s3, s38, s57
	s_and_b64 s[4:5], s[24:25], exec
	s_cselect_b32 s91, s3, 64
	s_or_b32 s3, s37, s56
	s_cmp_gt_u32 s3, 1
	s_cselect_b64 s[30:31], -1, 0
	s_lshl_b32 s4, s2, 6
	s_ashr_i32 s3, s2, 31
	s_ashr_i32 s5, s4, 31
	s_lshl_b64 s[34:35], s[2:3], 16
	s_lshl_b64 s[4:5], s[4:5], 12
	s_add_u32 s3, s4, 0x2000000
	s_addc_u32 s4, s5, 0
	s_lshl_b32 s6, s90, 8
	s_or_b32 s92, s34, s36
	s_lshl_b32 s36, s36, 8
	s_or_b32 s5, s3, s6
	s_lshl_b32 s2, s2, 11
	s_or_b32 s3, s3, s36
	s_add_u32 s36, s58, s5
	v_lshrrev_b32_e32 v8, 3, v3
	s_addc_u32 s37, s59, s4
	v_lshlrev_b32_e32 v7, 3, v3
	v_and_b32_e32 v8, 2, v8
	v_bfe_u32 v3, v3, 1, 1
	s_add_u32 s38, s52, s5
	v_lshrrev_b32_e32 v5, 2, v4
	v_or_b32_e32 v9, v8, v3
	v_bitop3_b32 v3, v8, v187, v3 bitop3:0x36
	s_addc_u32 s39, s53, s4
	v_lshlrev_b32_e32 v6, 8, v5
	v_lshlrev_b32_e32 v3, 4, v3
	v_lshlrev_b32_e32 v5, 6, v5
	s_add_u32 s40, s58, s3
	v_and_b32_e32 v7, 8, v7
	v_or_b32_e32 v171, v3, v5
	v_bitop3_b32 v189, v3, v5, 64 bitop3:0xf6
	v_bitop3_b32 v191, v3, v5, s74 bitop3:0xf6
	v_bitop3_b32 v193, v3, v5, s75 bitop3:0xf6
	v_lshlrev_b32_e32 v3, 10, v187
	s_addc_u32 s41, s59, s4
	v_or3_b32 v195, v3, v6, v7
	v_lshlrev_b32_e32 v196, 8, v2
	v_or_b32_e32 v2, s69, v187
	v_bitop3_b32 v3, v187, v4, s69 bitop3:0x36
	s_add_u32 s42, s52, s3
	v_bitop3_b32 v8, v187, v9, 2 bitop3:0x36
	v_lshlrev_b32_e32 v197, 4, v3
	v_bitop3_b32 v3, v2, v4, 2 bitop3:0x36
	s_addc_u32 s43, s53, s4
	s_lshl_b32 s3, s97, 7
	v_lshlrev_b32_e32 v8, 4, v8
	v_lshlrev_b32_e32 v198, 4, v3
	v_bitop3_b32 v3, v2, v4, 4 bitop3:0x36
	v_bitop3_b32 v2, v2, v4, 6 bitop3:0x36
	s_add_i32 s2, s2, s3
	v_mov_b32_e32 v50, v163
	v_mov_b32_e32 v51, v163
	v_mov_b32_e32 v64, v163
	v_mov_b32_e32 v65, v163
	v_or_b32_e32 v188, v8, v5
	v_bitop3_b32 v190, v8, v5, 64 bitop3:0xf6
	v_bitop3_b32 v192, v8, v5, s74 bitop3:0xf6
	v_bitop3_b32 v194, v8, v5, s75 bitop3:0xf6
	v_lshlrev_b32_e32 v199, 4, v3
	v_lshlrev_b32_e32 v200, 4, v2
	s_add_i32 s94, s44, 1
	s_add_i32 s44, s2, 0xc0
	s_lshl_b32 s2, s97, 10
	v_mov_b32_e32 v52, v163
	v_mov_b32_e32 v53, v163
	v_mov_b32_e32 v54, v163
	v_mov_b32_e32 v55, v163
	v_mov_b32_e32 v56, v163
	v_mov_b32_e32 v57, v163
	v_mov_b32_e32 v58, v163
	v_mov_b32_e32 v59, v163
	v_mov_b32_e32 v60, v163
	v_mov_b32_e32 v61, v163
	v_mov_b32_e32 v62, v163
	v_mov_b32_e32 v63, v163
	v_mov_b64_e32 v[34:35], v[50:51]
	v_mov_b64_e32 v[18:19], v[50:51]
	v_mov_b64_e32 v[2:3], v[50:51]
	v_mov_b64_e32 v[80:81], v[64:65]
	v_mov_b64_e32 v[112:113], v[64:65]
	s_mov_b32 s93, s35
	s_add_i32 s95, s2, 0x400
	v_mov_b32_e32 v170, 0xf149f2ca
	v_mov_b32_e32 v167, 0
	v_mov_b64_e32 v[36:37], v[52:53]
	v_mov_b64_e32 v[38:39], v[54:55]
	v_mov_b64_e32 v[40:41], v[56:57]
	v_mov_b64_e32 v[42:43], v[58:59]
	v_mov_b64_e32 v[44:45], v[60:61]
	v_mov_b64_e32 v[46:47], v[62:63]
	v_mov_b64_e32 v[48:49], v[64:65]
	v_mov_b64_e32 v[20:21], v[52:53]
	v_mov_b64_e32 v[22:23], v[54:55]
	v_mov_b64_e32 v[24:25], v[56:57]
	v_mov_b64_e32 v[26:27], v[58:59]
	v_mov_b64_e32 v[28:29], v[60:61]
	v_mov_b64_e32 v[30:31], v[62:63]
	v_mov_b64_e32 v[32:33], v[64:65]
	v_mov_b64_e32 v[4:5], v[52:53]
	v_mov_b64_e32 v[6:7], v[54:55]
	v_mov_b64_e32 v[8:9], v[56:57]
	v_mov_b64_e32 v[10:11], v[58:59]
	v_mov_b64_e32 v[12:13], v[60:61]
	v_mov_b64_e32 v[14:15], v[62:63]
	v_mov_b64_e32 v[16:17], v[64:65]
	v_mov_b64_e32 v[78:79], v[62:63]
	v_mov_b64_e32 v[76:77], v[60:61]
	v_mov_b64_e32 v[74:75], v[58:59]
	v_mov_b64_e32 v[72:73], v[56:57]
	v_mov_b64_e32 v[70:71], v[54:55]
	v_mov_b64_e32 v[68:69], v[52:53]
	v_mov_b64_e32 v[66:67], v[50:51]
	v_mov_b64_e32 v[110:111], v[62:63]
	v_mov_b64_e32 v[108:109], v[60:61]
	v_mov_b64_e32 v[106:107], v[58:59]
	v_mov_b64_e32 v[104:105], v[56:57]
	v_mov_b64_e32 v[102:103], v[54:55]
	v_mov_b64_e32 v[100:101], v[52:53]
	v_mov_b64_e32 v[98:99], v[50:51]
.LBB0_3301:
	s_add_i32 s96, s97, 1
	s_cmp_ge_i32 s96, s21
	s_cselect_b64 s[46:47], -1, 0
	s_and_b64 vcc, exec, s[46:47]
	s_cbranch_vccnz .Lpb19_done
	s_mov_b64 s[48:49], -1
	s_and_b64 vcc, exec, s[26:27]
	s_cbranch_vccz .Lpb19_a2
	s_cmp_gt_u32 s97, 62
	s_mov_b64 s[4:5], s[38:39]
	s_mov_b64 s[2:3], s[36:37]
	s_cbranch_scc1 .Lpb19_a1
	s_add_i32 s2, s90, s95
	s_or_b32 s2, s34, s2
	s_mov_b32 s3, s35
	s_lshl_b64 s[4:5], s[2:3], 8
	s_add_u32 s2, s62, s4
	s_addc_u32 s3, s63, s5
	s_add_u32 s4, s70, s4
	s_addc_u32 s5, s71, s5
